# banded attention tile body rescheduled: chained QK with bias and V LDS reads in MFMA shadows, single-base bias reads, deferred row sums
# speedup vs baseline: 1.0795x; 1.0013x over previous
.LBB0_398:
	v_lshlrev_b32_e32 v125, 2, v13
	v_lshrrev_b32_e32 v0, 2, v2
	v_and_or_b32 v0, v0, 3, v125
	v_mul_u32_u24_e32 v142, 0xc0, v0
	v_and_b32_e32 v0, 16, v2
	v_lshlrev_b32_e32 v2, 2, v2
	v_and_or_b32 v0, v2, 12, v0
	v_cmp_gt_u32_e64 s[36:37], 32, v14
	v_lshlrev_b32_e32 v144, 1, v0
	v_mov_b32_e32 v14, v1
	v_cndmask_b32_e64 v0, 0, 1.0, s[36:37]
	v_cndmask_b32_e64 v143, v0, 0, s[16:17]
	v_lshlrev_b32_e32 v0, 2, v12
	v_lshl_or_b32 v0, s31, 7, v0
	v_sub_u32_e32 v0, v0, v124
	v_mov_b32_e32 v15, v1
	s_waitcnt vmcnt(0)
	v_mul_u32_u24_e32 v141, 0xd0, v12
	s_min_u32 s8, s34, 2
	v_add_u32_e32 v145, 0, v0
	v_mov_b32_e32 v226, 0
	v_mov_b32_e32 v227, 0
	v_mov_b32_e32 v228, 0
	v_mov_b32_e32 v229, 0
	v_mov_b32_e32 v230, 0
	v_mov_b32_e32 v231, 0
	v_mov_b32_e32 v232, 0
	v_mov_b32_e32 v233, 0
	v_mov_b32_e32 v234, 0
	v_mov_b32_e32 v235, 0
	v_mov_b32_e32 v236, 0
	v_mov_b32_e32 v237, 0
	v_mov_b32_e32 v238, 0
	v_mov_b32_e32 v239, 0
	v_mov_b32_e32 v240, 0
	v_mov_b32_e32 v241, 0
	v_mov_b32_e32 v242, 0
	v_mov_b32_e32 v243, 0
	v_mov_b32_e32 v244, 0
	v_mov_b32_e32 v245, 0
	v_mov_b32_e32 v246, 0
	v_mov_b32_e32 v247, 0
	v_mov_b32_e32 v248, 0
	v_mov_b32_e32 v249, 0
	v_mov_b32_e32 v166, 0
	v_mov_b32_e32 v167, 0
	v_mov_b32_e32 v168, 0
	v_mov_b32_e32 v169, 0
	v_mov_b32_e32 v170, 0
	v_mov_b32_e32 v171, 0
	v_mov_b32_e32 v172, 0
	v_mov_b32_e32 v173, 0
	v_mov_b32_e32 v0, v1
	v_mov_b32_e32 v2, v1
	v_mov_b32_e32 v3, v1
	v_mov_b32_e32 v4, v1
	v_mov_b32_e32 v5, v1
	v_mov_b32_e32 v6, v1
	v_mov_b32_e32 v7, v1
	v_mov_b32_e32 v8, v1
	v_mov_b32_e32 v9, v1
	v_mov_b32_e32 v10, v1
	v_mov_b32_e32 v11, v1
	v_mov_b32_e32 v12, v1
	v_mov_b32_e32 v13, v1
	v_mov_b64_e32 v[32:33], v[14:15]
	s_or_b32 s7, s34, 3
	s_or_b32 s5, s20, 31
	s_add_i32 s13, s20, s13
	s_lshl_b32 s20, s8, 8
	s_lshl_b32 s8, s8, 6
	v_mov_b64_e32 v[30:31], v[12:13]
	v_mov_b64_e32 v[28:29], v[10:11]
	v_mov_b64_e32 v[26:27], v[8:9]
	v_mov_b64_e32 v[24:25], v[6:7]
	v_mov_b64_e32 v[22:23], v[4:5]
	v_mov_b64_e32 v[20:21], v[2:3]
	v_mov_b64_e32 v[18:19], v[0:1]
	v_mov_b64_e32 v[16:17], v[14:15]
	s_sub_i32 s7, s7, s1
	s_sub_i32 s30, s30, s8
	s_mov_b32 s31, 0
	s_movk_i32 s34, 0xfc00
	v_mov_b64_e32 v[14:15], v[12:13]
	v_mov_b64_e32 v[12:13], v[10:11]
	v_mov_b64_e32 v[10:11], v[8:9]
	v_mov_b64_e32 v[8:9], v[6:7]
	v_mov_b64_e32 v[6:7], v[4:5]
	v_mov_b64_e32 v[4:5], v[2:3]
	v_mov_b64_e32 v[2:3], v[0:1]
	s_waitcnt vmcnt(0) lgkmcnt(0)
	s_barrier
	s_branch .LBB0_400

.LBB0_407:
	s_xor_b64 s[50:51], s[50:51], -1
	s_andn2_b64 vcc, exec, s[50:51]
	s_cbranch_vccnz .LBB0_418
	s_and_b32 s8, s31, 3
	s_mulk_i32 s8, 0x6400
	s_add_i32 s8, s8, 0
	v_add3_u32 v0, s8, v141, v124
	ds_read_b128 v[158:161], v0
	ds_read_b128 v[126:129], v0 offset:32
	ds_read_b128 v[134:137], v0 offset:64
	ds_read_b128 v[146:149], v0 offset:96
	ds_read_b128 v[162:165], v0 offset:6656
	ds_read_b128 v[130:133], v0 offset:6688
	ds_read_b128 v[150:153], v0 offset:6720
	ds_read_b128 v[154:157], v0 offset:6752
	v_add3_u32 v253, s8, v142, v144
	v_add_u32_e32 v182, s20, v145
	v_add_u32_e32 v182, 0x19114, v182
	s_andn2_b64 vcc, exec, s[16:17]
	s_cbranch_vccnz .Le2_nodma
	s_add_i32 s35, s31, 2
	s_cmp_gt_u32 s35, s7
	s_cbranch_scc1 .Le2_d2
	s_and_b32 s8, s35, 2
	s_mulk_i32 s8, 0x6400
	s_add_i32 s35, s8, 0
	s_add_i32 s8, s35, s4
	s_mov_b32 m0, s8
	s_and_b64 vcc, exec, s[38:39]
	global_load_lds_dwordx4 v[66:67], off
	s_add_i32 m0, s8, 0x2000
	v_lshl_add_u64 v[66:67], v[66:67], 0, s[14:15]
	global_load_lds_dwordx4 v[68:69], off
	s_add_i32 m0, s8, 0x4000
	v_lshl_add_u64 v[68:69], v[68:69], 0, s[14:15]
	global_load_lds_dwordx4 v[70:71], off
	v_lshl_add_u64 v[70:71], v[70:71], 0, s[14:15]
	s_cbranch_vccnz .Le2_d2
	s_add_i32 m0, s35, 0x6000
	v_lshl_add_u64 v[254:255], v[72:73], 0, s[14:15]
	global_load_lds_dwordx4 v[72:73], off
	v_mov_b32_e32 v72, v254
	v_mov_b32_e32 v73, v255
.Le2_d2:
	s_add_i32 s35, s31, 3
	s_cmp_gt_u32 s35, s7
	s_cbranch_scc1 .Le2_nodma
	s_and_b32 s8, s35, 3
	s_mulk_i32 s8, 0x6400
	s_add_i32 s35, s8, 0
	s_add_i32 s8, s35, s4
	s_mov_b32 m0, s8
	s_and_b64 vcc, exec, s[38:39]
	global_load_lds_dwordx4 v[66:67], off
	s_add_i32 m0, s8, 0x2000
	v_lshl_add_u64 v[66:67], v[66:67], 0, s[14:15]
	global_load_lds_dwordx4 v[68:69], off
	s_add_i32 m0, s8, 0x4000
	v_lshl_add_u64 v[68:69], v[68:69], 0, s[14:15]
	global_load_lds_dwordx4 v[70:71], off
	v_lshl_add_u64 v[70:71], v[70:71], 0, s[14:15]
	s_cbranch_vccnz .Le2_nodma
	s_add_i32 m0, s35, 0x6000
	v_lshl_add_u64 v[254:255], v[72:73], 0, s[14:15]
	global_load_lds_dwordx4 v[72:73], off
	v_mov_b32_e32 v72, v254
	v_mov_b32_e32 v73, v255
.Le2_nodma:
	s_waitcnt lgkmcnt(7)
	v_mfma_f32_32x32x16_bf16 v[50:65], v[158:161], v[74:77], 0
	ds_read2_b32 v[194:195], v182 offset0:58 offset1:59
	ds_read2_b32 v[196:197], v182 offset0:56 offset1:57
	ds_read2_b32 v[198:199], v182 offset0:50 offset1:51
	v_add_f32_e32 v254, v226, v227
	v_add_f32_e32 v255, v228, v229
	v_add_f32_e32 v254, v254, v230
	s_waitcnt lgkmcnt(9)
	v_mfma_f32_32x32x16_bf16 v[50:65], v[126:129], v[78:81], v[50:65]
	ds_read2_b32 v[200:201], v182 offset0:48 offset1:49
	ds_read2_b32 v[202:203], v182 offset0:42 offset1:43
	ds_read2_b32 v[204:205], v182 offset0:40 offset1:41
	v_add_f32_e32 v255, v255, v231
	v_add_f32_e32 v254, v254, v232
	v_add_f32_e32 v255, v255, v233
	s_waitcnt lgkmcnt(11)
	v_mfma_f32_32x32x16_bf16 v[50:65], v[134:137], v[82:85], v[50:65]
	ds_read2_b32 v[206:207], v182 offset0:34 offset1:35
	ds_read2_b32 v[208:209], v182 offset0:32 offset1:33
	ds_read2_b32 v[210:211], v182 offset0:26 offset1:27
	v_add_f32_e32 v254, v254, v234
	v_add_f32_e32 v255, v255, v235
	v_add_f32_e32 v254, v254, v236
	s_waitcnt lgkmcnt(13)
	v_mfma_f32_32x32x16_bf16 v[50:65], v[146:149], v[86:89], v[50:65]
	ds_read2_b32 v[212:213], v182 offset0:24 offset1:25
	ds_read2_b32 v[214:215], v182 offset0:18 offset1:19
	s_waitcnt lgkmcnt(14)
	ds_read2_b32 v[216:217], v182 offset0:16 offset1:17
	v_add_f32_e32 v255, v255, v237
	v_add_f32_e32 v254, v254, v238
	v_add_f32_e32 v255, v255, v239
	v_mfma_f32_32x32x16_bf16 v[34:49], v[162:165], v[74:77], 0
	s_waitcnt lgkmcnt(14)
	ds_read2_b32 v[218:219], v182 offset0:10 offset1:11
	s_waitcnt lgkmcnt(14)
	ds_read2_b32 v[220:221], v182 offset0:8 offset1:9
	v_add_f32_e32 v254, v254, v240
	v_add_f32_e32 v255, v255, v241
	v_add_f32_e32 v254, v254, v242
	v_add_f32_e32 v255, v255, v243
	v_mfma_f32_32x32x16_bf16 v[34:49], v[130:133], v[78:81], v[34:49]
	s_waitcnt lgkmcnt(14)
	ds_read2_b32 v[222:223], v182 offset0:2 offset1:3
	s_waitcnt lgkmcnt(14)
	ds_read2_b32 v[224:225], v182 offset0:0 offset1:1
	v_add_f32_e32 v254, v254, v244
	v_add_f32_e32 v255, v255, v245
	v_add_f32_e32 v254, v254, v246
	v_add_f32_e32 v255, v255, v247
	v_mfma_f32_32x32x16_bf16 v[34:49], v[150:153], v[82:85], v[34:49]
	s_waitcnt lgkmcnt(13)
	v_fmamk_f32 v50, v50, 0x3e38aa3b, v195
	v_fmamk_f32 v51, v51, 0x3e38aa3b, v194
	v_fmamk_f32 v52, v52, 0x3e38aa3b, v197
	v_fmamk_f32 v53, v53, 0x3e38aa3b, v196
	v_fmamk_f32 v54, v54, 0x3e38aa3b, v199
	v_fmamk_f32 v55, v55, 0x3e38aa3b, v198
	v_mfma_f32_32x32x16_bf16 v[34:49], v[154:157], v[86:89], v[34:49]
	s_waitcnt lgkmcnt(10)
	v_fmamk_f32 v56, v56, 0x3e38aa3b, v201
	v_fmamk_f32 v57, v57, 0x3e38aa3b, v200
	v_fmamk_f32 v58, v58, 0x3e38aa3b, v203
	v_fmamk_f32 v59, v59, 0x3e38aa3b, v202
	v_fmamk_f32 v60, v60, 0x3e38aa3b, v205
	v_fmamk_f32 v61, v61, 0x3e38aa3b, v204
	s_waitcnt lgkmcnt(8)
	v_fmamk_f32 v62, v62, 0x3e38aa3b, v207
	v_fmamk_f32 v63, v63, 0x3e38aa3b, v206
	v_fmamk_f32 v64, v64, 0x3e38aa3b, v209
	v_fmamk_f32 v65, v65, 0x3e38aa3b, v208
	v_add_f32_e32 v254, v254, v248
	v_add_f32_e32 v255, v255, v249
	v_add_f32_e32 v254, v254, v166
	v_add_f32_e32 v255, v255, v167
	v_add_f32_e32 v254, v254, v168
	v_add_f32_e32 v255, v255, v169
	v_max3_f32 v183, v50, v51, v52
	v_max3_f32 v183, v183, v53, v54
	v_max3_f32 v183, v183, v55, v56
	v_max3_f32 v183, v183, v57, v58
	v_max3_f32 v183, v183, v59, v60
	v_max3_f32 v183, v183, v61, v62
	v_max3_f32 v183, v183, v63, v64
	v_max3_f32 v183, v183, v65, v65
	v_add_f32_e32 v254, v254, v170
	v_add_f32_e32 v255, v255, v171
	v_add_f32_e32 v254, v254, v172
	v_add_f32_e32 v255, v255, v173
	v_add_f32_e32 v254, v254, v255
	v_add_f32_e32 v143, v143, v254
	ds_read_b64_tr_b16 v[118:119], v253 offset:13312
	ds_read_b64_tr_b16 v[120:121], v253 offset:14848
	ds_read_b64_tr_b16 v[116:117], v253 offset:14912
	ds_read_b64_tr_b16 v[114:115], v253 offset:13376
	ds_read_b64_tr_b16 v[110:111], v253 offset:16384
	ds_read_b64_tr_b16 v[112:113], v253 offset:17920
	ds_read_b64_tr_b16 v[108:109], v253 offset:17984
	s_waitcnt lgkmcnt(14)
	ds_read_b64_tr_b16 v[106:107], v253 offset:16448
	s_waitcnt lgkmcnt(8)
	v_fmamk_f32 v34, v34, 0x3e38aa3b, v211
	v_fmamk_f32 v35, v35, 0x3e38aa3b, v210
	v_fmamk_f32 v36, v36, 0x3e38aa3b, v213
	v_fmamk_f32 v37, v37, 0x3e38aa3b, v212
	v_fmamk_f32 v38, v38, 0x3e38aa3b, v215
	v_fmamk_f32 v39, v39, 0x3e38aa3b, v214
	v_fmamk_f32 v40, v40, 0x3e38aa3b, v217
	v_fmamk_f32 v41, v41, 0x3e38aa3b, v216
	v_fmamk_f32 v42, v42, 0x3e38aa3b, v219
	v_fmamk_f32 v43, v43, 0x3e38aa3b, v218
	v_fmamk_f32 v44, v44, 0x3e38aa3b, v221
	v_fmamk_f32 v45, v45, 0x3e38aa3b, v220
	v_fmamk_f32 v46, v46, 0x3e38aa3b, v223
	v_fmamk_f32 v47, v47, 0x3e38aa3b, v222
	v_fmamk_f32 v48, v48, 0x3e38aa3b, v225
	v_fmamk_f32 v49, v49, 0x3e38aa3b, v224
	ds_read_b64_tr_b16 v[102:103], v253 offset:19456
	ds_read_b64_tr_b16 v[104:105], v253 offset:20992
	ds_read_b64_tr_b16 v[100:101], v253 offset:21056
	ds_read_b64_tr_b16 v[98:99], v253 offset:19520
	ds_read_b64_tr_b16 v[94:95], v253 offset:22528
	ds_read_b64_tr_b16 v[96:97], v253 offset:24064
	ds_read_b64_tr_b16 v[92:93], v253 offset:24128
	s_waitcnt lgkmcnt(14)
	ds_read_b64_tr_b16 v[90:91], v253 offset:22592
	v_max3_f32 v182, v34, v35, v36
	v_max3_f32 v182, v182, v37, v38
	v_max3_f32 v182, v182, v39, v40
	v_max3_f32 v182, v182, v41, v42
	v_max3_f32 v182, v182, v43, v44
	v_max3_f32 v182, v182, v45, v46
	v_max3_f32 v182, v182, v47, v48
	v_max3_f32 v182, v182, v49, v49
	s_nop 0
	v_max_f32_e32 v182, v182, v182
	v_max_f32_e32 v183, v183, v183
	v_max_f32_e32 v183, v183, v182
	v_sub_f32_e32 v182, v183, v140
	v_cmp_lt_f32_e32 vcc, s21, v182
	s_cbranch_vccnz .Le2_rescale
.Le2_ok:
	s_waitcnt lgkmcnt(0)
	v_sub_f32_e32 v226, v50, v140
	v_exp_f32_e32 v226, v226
	v_sub_f32_e32 v227, v51, v140
	v_exp_f32_e32 v227, v227
	v_sub_f32_e32 v228, v52, v140
	v_exp_f32_e32 v228, v228
	v_sub_f32_e32 v229, v53, v140
	v_exp_f32_e32 v229, v229
	v_sub_f32_e32 v230, v54, v140
	v_exp_f32_e32 v230, v230
	v_sub_f32_e32 v231, v55, v140
	v_exp_f32_e32 v231, v231
	v_sub_f32_e32 v232, v56, v140
	v_exp_f32_e32 v232, v232
	v_sub_f32_e32 v233, v57, v140
	v_exp_f32_e32 v233, v233
	v_cvt_pk_bf16_f32 v174, v226, v227
	v_cvt_pk_bf16_f32 v175, v228, v229
	v_cvt_pk_bf16_f32 v176, v230, v231
	v_cvt_pk_bf16_f32 v177, v232, v233
	s_nop 1
	v_mfma_f32_32x32x16_bf16 v[18:33], v[118:121], v[174:177], v[18:33]
	v_sub_f32_e32 v234, v58, v140
	v_exp_f32_e32 v234, v234
	v_sub_f32_e32 v235, v59, v140
	v_exp_f32_e32 v235, v235
	v_mfma_f32_32x32x16_bf16 v[2:17], v[114:117], v[174:177], v[2:17]
	v_sub_f32_e32 v236, v60, v140
	v_exp_f32_e32 v236, v236
	v_sub_f32_e32 v237, v61, v140
	v_exp_f32_e32 v237, v237
	v_sub_f32_e32 v238, v62, v140
	v_exp_f32_e32 v238, v238
	v_sub_f32_e32 v239, v63, v140
	v_exp_f32_e32 v239, v239
	v_sub_f32_e32 v240, v64, v140
	v_exp_f32_e32 v240, v240
	v_sub_f32_e32 v241, v65, v140
	v_exp_f32_e32 v241, v241
	v_cvt_pk_bf16_f32 v178, v234, v235
	v_cvt_pk_bf16_f32 v179, v236, v237
	v_cvt_pk_bf16_f32 v180, v238, v239
	v_cvt_pk_bf16_f32 v181, v240, v241
	s_nop 1
	v_mfma_f32_32x32x16_bf16 v[18:33], v[110:113], v[178:181], v[18:33]
	v_sub_f32_e32 v242, v34, v140
	v_exp_f32_e32 v242, v242
	v_sub_f32_e32 v243, v35, v140
	v_exp_f32_e32 v243, v243
	v_mfma_f32_32x32x16_bf16 v[2:17], v[106:109], v[178:181], v[2:17]
	v_sub_f32_e32 v244, v36, v140
	v_exp_f32_e32 v244, v244
	v_sub_f32_e32 v245, v37, v140
	v_exp_f32_e32 v245, v245
	v_sub_f32_e32 v246, v38, v140
	v_exp_f32_e32 v246, v246
	v_sub_f32_e32 v247, v39, v140
	v_exp_f32_e32 v247, v247
	v_sub_f32_e32 v248, v40, v140
	v_exp_f32_e32 v248, v248
	v_sub_f32_e32 v249, v41, v140
	v_exp_f32_e32 v249, v249
	v_cvt_pk_bf16_f32 v174, v242, v243
	v_cvt_pk_bf16_f32 v175, v244, v245
	v_cvt_pk_bf16_f32 v176, v246, v247
	v_cvt_pk_bf16_f32 v177, v248, v249
	s_nop 1
	v_mfma_f32_32x32x16_bf16 v[18:33], v[102:105], v[174:177], v[18:33]
	v_sub_f32_e32 v166, v42, v140
	v_exp_f32_e32 v166, v166
	v_sub_f32_e32 v167, v43, v140
	v_exp_f32_e32 v167, v167
	v_mfma_f32_32x32x16_bf16 v[2:17], v[98:101], v[174:177], v[2:17]
	v_sub_f32_e32 v168, v44, v140
	v_exp_f32_e32 v168, v168
	v_sub_f32_e32 v169, v45, v140
	v_exp_f32_e32 v169, v169
	v_sub_f32_e32 v170, v46, v140
	v_exp_f32_e32 v170, v170
	v_sub_f32_e32 v171, v47, v140
	v_exp_f32_e32 v171, v171
	v_sub_f32_e32 v172, v48, v140
	v_exp_f32_e32 v172, v172
	v_sub_f32_e32 v173, v49, v140
	v_exp_f32_e32 v173, v173
	v_cvt_pk_bf16_f32 v178, v166, v167
	v_cvt_pk_bf16_f32 v179, v168, v169
	v_cvt_pk_bf16_f32 v180, v170, v171
	v_cvt_pk_bf16_f32 v181, v172, v173
	s_nop 1
	v_mfma_f32_32x32x16_bf16 v[18:33], v[94:97], v[178:181], v[18:33]
	v_mfma_f32_32x32x16_bf16 v[2:17], v[90:93], v[178:181], v[2:17]
	s_branch .LBB0_418
.Le2_rescale:
	v_xor_b32_e32 v254, 32, v187
	v_cmp_lt_i32_e32 vcc, v254, v189
	s_nop 1
	v_cndmask_b32_e32 v254, v187, v254, vcc
	v_lshlrev_b32_e32 v254, 2, v254
	ds_bpermute_b32 v254, v254, v183
	s_waitcnt lgkmcnt(0)
	v_max3_f32 v183, v140, v183, v254
	v_sub_f32_e32 v254, v140, v183
	v_exp_f32_e32 v254, v254
	v_mov_b32_e32 v140, v183
	v_pk_mul_f32 v[32:33], v[32:33], v[254:255] op_sel_hi:[1,0]
	v_pk_mul_f32 v[30:31], v[30:31], v[254:255] op_sel_hi:[1,0]
	v_pk_mul_f32 v[28:29], v[28:29], v[254:255] op_sel_hi:[1,0]
	v_pk_mul_f32 v[26:27], v[26:27], v[254:255] op_sel_hi:[1,0]
	v_pk_mul_f32 v[24:25], v[24:25], v[254:255] op_sel_hi:[1,0]
	v_pk_mul_f32 v[22:23], v[22:23], v[254:255] op_sel_hi:[1,0]
	v_pk_mul_f32 v[20:21], v[20:21], v[254:255] op_sel_hi:[1,0]
	v_pk_mul_f32 v[18:19], v[18:19], v[254:255] op_sel_hi:[1,0]
	v_pk_mul_f32 v[16:17], v[16:17], v[254:255] op_sel_hi:[1,0]
	v_pk_mul_f32 v[14:15], v[14:15], v[254:255] op_sel_hi:[1,0]
	v_pk_mul_f32 v[12:13], v[12:13], v[254:255] op_sel_hi:[1,0]
	v_pk_mul_f32 v[10:11], v[10:11], v[254:255] op_sel_hi:[1,0]
	v_pk_mul_f32 v[8:9], v[8:9], v[254:255] op_sel_hi:[1,0]
	v_pk_mul_f32 v[6:7], v[6:7], v[254:255] op_sel_hi:[1,0]
	v_pk_mul_f32 v[4:5], v[4:5], v[254:255] op_sel_hi:[1,0]
	v_pk_mul_f32 v[2:3], v[2:3], v[254:255] op_sel_hi:[1,0]
	v_mul_f32_e32 v143, v143, v254
	s_branch .Le2_ok

.LBB0_420:
	v_add_f32_e32 v254, v226, v227
	v_add_f32_e32 v255, v228, v229
	v_add_f32_e32 v254, v254, v230
	v_add_f32_e32 v255, v255, v231
	v_add_f32_e32 v254, v254, v232
	v_add_f32_e32 v255, v255, v233
	v_add_f32_e32 v254, v254, v234
	v_add_f32_e32 v255, v255, v235
	v_add_f32_e32 v254, v254, v236
	v_add_f32_e32 v255, v255, v237
	v_add_f32_e32 v254, v254, v238
	v_add_f32_e32 v255, v255, v239
	v_add_f32_e32 v254, v254, v240
	v_add_f32_e32 v255, v255, v241
	v_add_f32_e32 v254, v254, v242
	v_add_f32_e32 v255, v255, v243
	v_add_f32_e32 v254, v254, v244
	v_add_f32_e32 v255, v255, v245
	v_add_f32_e32 v254, v254, v246
	v_add_f32_e32 v255, v255, v247
	v_add_f32_e32 v254, v254, v248
	v_add_f32_e32 v255, v255, v249
	v_add_f32_e32 v254, v254, v166
	v_add_f32_e32 v255, v255, v167
	v_add_f32_e32 v254, v254, v168
	v_add_f32_e32 v255, v255, v169
	v_add_f32_e32 v254, v254, v170
	v_add_f32_e32 v255, v255, v171
	v_add_f32_e32 v254, v254, v172
	v_add_f32_e32 v255, v255, v173
	v_add_f32_e32 v254, v254, v255
	v_add_f32_e32 v143, v143, v254
	v_xor_b32_e32 v0, 32, v187
	v_cmp_lt_i32_e32 vcc, v0, v189
	s_cmp_lg_u64 s[40:41], 0
	s_nop 0
	v_cndmask_b32_e32 v0, v187, v0, vcc
	v_lshlrev_b32_e32 v0, 2, v0
	ds_bpermute_b32 v0, v0, v143
	s_waitcnt lgkmcnt(0)
	v_add_f32_e32 v34, v143, v0
	v_div_scale_f32 v0, s[4:5], v34, v34, 1.0
	v_rcp_f32_e32 v35, v0
	s_nop 0
	v_fma_f32 v36, -v0, v35, 1.0
	v_fmac_f32_e32 v35, v36, v35
	v_div_scale_f32 v36, vcc, 1.0, v34, 1.0
	v_mul_f32_e32 v37, v36, v35
	v_fma_f32 v38, -v0, v37, v36
	v_fmac_f32_e32 v37, v38, v35
	v_fma_f32 v0, -v0, v37, v36
	v_div_fmas_f32 v0, v0, v35, v37
	v_mad_u64_u32 v[36:37], s[4:5], v122, s46, 0
	v_mad_i32_i24 v37, v123, s46, v37
	v_div_fixup_f32 v35, v0, v34, 1.0
	v_lshl_add_u64 v[36:37], v[36:37], 1, s[44:45]
	v_lshlrev_b32_e32 v0, 1, v125
	v_lshl_add_u64 v[36:37], v[36:37], 0, v[0:1]
	v_mul_f32_e32 v0, v18, v35
	v_mul_f32_e32 v18, v19, v35
	v_cvt_pk_bf16_f32 v18, v0, v18
	v_mul_f32_e32 v0, v20, v35
	v_mul_f32_e32 v19, v21, v35
	v_cvt_pk_bf16_f32 v19, v0, v19
	v_mul_f32_e32 v0, v2, v35
	v_mul_f32_e32 v2, v3, v35
	v_cvt_pk_bf16_f32 v2, v0, v2
	v_mul_f32_e32 v0, v4, v35
	v_mul_f32_e32 v3, v5, v35
	v_cvt_pk_bf16_f32 v3, v0, v3
	global_store_dwordx2 v[36:37], v[18:19], off
	global_store_dwordx2 v[36:37], v[2:3], off offset:64
	v_mul_f32_e32 v0, v22, v35
	v_mul_f32_e32 v2, v23, v35
	v_cvt_pk_bf16_f32 v2, v0, v2
	v_mul_f32_e32 v0, v24, v35
	v_mul_f32_e32 v3, v25, v35
	v_cvt_pk_bf16_f32 v3, v0, v3
	v_mul_f32_e32 v0, v6, v35
	v_mul_f32_e32 v4, v7, v35
	v_cvt_pk_bf16_f32 v4, v0, v4
	v_mul_f32_e32 v0, v8, v35
	v_mul_f32_e32 v5, v9, v35
	v_cvt_pk_bf16_f32 v5, v0, v5
	global_store_dwordx2 v[36:37], v[2:3], off offset:16
	global_store_dwordx2 v[36:37], v[4:5], off offset:80
	v_mul_f32_e32 v0, v26, v35
	v_mul_f32_e32 v2, v27, v35
	v_cvt_pk_bf16_f32 v2, v0, v2
	v_mul_f32_e32 v0, v28, v35
	v_mul_f32_e32 v3, v29, v35
	v_cvt_pk_bf16_f32 v3, v0, v3
	v_mul_f32_e32 v0, v10, v35
	v_mul_f32_e32 v4, v11, v35
	v_cvt_pk_bf16_f32 v4, v0, v4
	v_mul_f32_e32 v0, v12, v35
	v_mul_f32_e32 v5, v13, v35
	v_cvt_pk_bf16_f32 v5, v0, v5
	global_store_dwordx2 v[36:37], v[2:3], off offset:32
	global_store_dwordx2 v[36:37], v[4:5], off offset:96
	v_mul_f32_e32 v0, v30, v35
	v_mul_f32_e32 v2, v31, v35
	v_cvt_pk_bf16_f32 v2, v0, v2
	v_mul_f32_e32 v0, v32, v35
	v_mul_f32_e32 v3, v33, v35
	s_cselect_b64 s[4:5], -1, 0
	v_cvt_pk_bf16_f32 v3, v0, v3
	v_mul_f32_e32 v0, v14, v35
	v_mul_f32_e32 v4, v15, v35
	v_mul_f32_e32 v5, v17, v35
	s_and_b64 s[4:5], s[4:5], s[36:37]
	v_cvt_pk_bf16_f32 v4, v0, v4
	v_mul_f32_e32 v0, v16, v35
	v_cvt_pk_bf16_f32 v5, v0, v5
	global_store_dwordx2 v[36:37], v[2:3], off offset:48
	global_store_dwordx2 v[36:37], v[4:5], off offset:112
	s_and_saveexec_b64 s[16:17], s[4:5]
	s_cbranch_execz .LBB0_363
	v_log_f32_e32 v0, v34
	v_mad_u64_u32 v[2:3], s[4:5], v122, s42, 0
	v_mad_i32_i24 v3, v123, s42, v3
	v_add_f32_e32 v0, v140, v0
	v_mul_f32_e32 v0, 0x3f317218, v0
	v_lshl_add_u64 v[2:3], v[2:3], 2, s[40:41]
	global_store_dword v[2:3], v0, off
	s_branch .LBB0_363
